# first-half LDS-DMA issue interleaved into the MFMA stream (3 chunks after MFMA 4, 8, 12)
# speedup vs baseline: 1.0169x; 1.0033x over previous
; #define G_LOAD(RA, RB, k_) do { \
;     _Pragma("unroll") for (int i = 0; i < 4; ++i) RA[i] = *(const u32x4*)&Ap[i * sa + (k_)]; \
;     _Pragma("unroll") for (int i = 0; i < 2 * NJ; ++i) RB[i] = *(const u32x4*)&Bp[i * sbb + (k_)]; } while (0)
; template <int NJ>
; DI void gemm_core(const h16* __restrict__ A, int lda, const h16* __restrict__ Bt, int ldb, int K,
;                   floatx16 (&acc)[2][NJ], h16* As, h16* Bs) {
;     ...
;   G_LOAD(ra0, rb0, 0);
;   if (64 < K) G_LOAD(ra1, rb1, 64);
;   for (int k0 = 0; k0 < K; k0 += 128) {
;     G_STEP(ra0, rb0, k0 + 128);
;     if (k0 + 64 < K) G_STEP(ra1, rb1, k0 + 192);
;   }
; __global__ void __launch_bounds__(256, 2) mega(Params p) {
;     ...
;     if (PH(1)) for (int lj = xj.r; lj < 64 * 3; lj += xj.nrank) {
;       int mt, nt; xjob_map(xj, lj, 512, 3, mt, nt); const int m0 = mt * 128;
;       floatx16 acc[2][2]; acc_zero<2>(acc);
;       gemm_core<2>(x16 + (size_t)m0 * 1024, 1024, Wt + WT_IN + (size_t)(2048 + nt * 128) * 1024, 1024, 1024, acc, As, Bs);
;       epi_apply<2>(acc, [&](int r, int c, float v) { zpass[(size_t)(m0 + r) * 384 + nt * 128 + c] = (h16)v; });
;     }
.LBB0_128:
	ds_read_b128 v[142:145], v190 offset:512
	ds_read_b128 v[146:149], v191 offset:512
	ds_read_b128 v[166:169], v190 offset:4608
	ds_read_b128 v[170:173], v191 offset:4608
	ds_read_b128 v[174:177], v194 offset:16896
	ds_read_b128 v[178:181], v195 offset:16896
	ds_read_b128 v[182:185], v194 offset:20992
	ds_read_b128 v[186:189], v195 offset:20992
	s_waitcnt lgkmcnt(3)
	v_mfma_f32_32x32x16_f16 v[48:63], v[142:145], v[174:177], v[48:63]
	s_waitcnt lgkmcnt(1)
	v_mfma_f32_32x32x16_f16 v[32:47], v[142:145], v[182:185], v[32:47]
	v_mfma_f32_32x32x16_f16 v[16:31], v[166:169], v[174:177], v[16:31]
	v_mfma_f32_32x32x16_f16 v[0:15], v[166:169], v[182:185], v[0:15]
	v_add_co_u32_e32 v76, vcc, 0x10000, v136
	s_add_u32 m0, s100, 41856
	s_nop 0
	global_load_lds_dwordx4 v[136:137], off offset:128
	s_nop 0
	v_addc_co_u32_e32 v77, vcc, 0, v137, vcc
	v_add_co_u32_e32 v84, vcc, 0x20000, v136
	s_nop 1
	v_addc_co_u32_e32 v85, vcc, 0, v137, vcc
	v_add_co_u32_e32 v92, vcc, 0x30000, v136
	s_add_u32 m0, s100, 45952
	s_nop 0
	global_load_lds_dwordx4 v[76:77], off offset:128
	s_nop 0
	s_add_u32 m0, s100, 50048
	s_nop 0
	global_load_lds_dwordx4 v[84:85], off offset:128
	ds_read_b128 v[142:145], v192 offset:512
	ds_read_b128 v[166:169], v192 offset:4608
	ds_read_b128 v[174:177], v196 offset:16896
	ds_read_b128 v[182:185], v196 offset:20992
	v_mfma_f32_32x32x16_f16 v[48:63], v[146:149], v[178:181], v[48:63]
	s_waitcnt lgkmcnt(4)
	v_mfma_f32_32x32x16_f16 v[32:47], v[146:149], v[186:189], v[32:47]
	v_mfma_f32_32x32x16_f16 v[16:31], v[170:173], v[178:181], v[16:31]
	v_mfma_f32_32x32x16_f16 v[0:15], v[170:173], v[186:189], v[0:15]
	v_addc_co_u32_e32 v93, vcc, 0, v137, vcc
	v_add_co_u32_e32 v100, vcc, 0x400000, v134
	s_add_u32 m0, s100, 54144
	s_nop 0
	global_load_lds_dwordx4 v[92:93], off offset:128
	s_nop 0
	v_addc_co_u32_e32 v101, vcc, 0, v135, vcc
	v_add_co_u32_e32 v108, vcc, 0x410000, v134
	s_nop 1
	v_addc_co_u32_e32 v109, vcc, 0, v135, vcc
	v_add_co_u32_e32 v116, vcc, 0x420000, v134
	s_add_u32 m0, s100, 58240
	s_nop 0
	global_load_lds_dwordx4 v[100:101], off offset:128
	s_nop 0
	s_add_u32 m0, s100, 62336
	s_nop 0
	global_load_lds_dwordx4 v[108:109], off offset:128
	ds_read_b128 v[146:149], v193 offset:512
	ds_read_b128 v[170:173], v193 offset:4608
	ds_read_b128 v[178:181], v197 offset:16896
	ds_read_b128 v[186:189], v197 offset:20992
	s_waitcnt lgkmcnt(5)
	v_mfma_f32_32x32x16_f16 v[48:63], v[142:145], v[174:177], v[48:63]
	s_waitcnt lgkmcnt(4)
	v_mfma_f32_32x32x16_f16 v[32:47], v[142:145], v[182:185], v[32:47]
	v_mfma_f32_32x32x16_f16 v[16:31], v[166:169], v[174:177], v[16:31]
	v_mfma_f32_32x32x16_f16 v[0:15], v[166:169], v[182:185], v[0:15]
	v_addc_co_u32_e32 v117, vcc, 0, v135, vcc
	v_add_co_u32_e32 v124, vcc, 0x430000, v134
	s_nop 1
	v_addc_co_u32_e32 v125, vcc, 0, v135, vcc
	s_add_u32 m0, s100, 66432
	s_nop 0
	global_load_lds_dwordx4 v[116:117], off offset:128
	s_nop 0
	s_add_u32 m0, s100, 70528
	s_nop 0
	global_load_lds_dwordx4 v[124:125], off offset:128
	s_waitcnt lgkmcnt(1)
	v_mfma_f32_32x32x16_f16 v[48:63], v[146:149], v[178:181], v[48:63]
	s_waitcnt lgkmcnt(0)
	v_mfma_f32_32x32x16_f16 v[32:47], v[146:149], v[186:189], v[32:47]
	v_mfma_f32_32x32x16_f16 v[16:31], v[170:173], v[178:181], v[16:31]
	v_mfma_f32_32x32x16_f16 v[0:15], v[170:173], v[186:189], v[0:15]
	s_waitcnt vmcnt(0)
	s_barrier
	s_and_b64 vcc, exec, s[40:41]
	s_cbranch_vccnz .LBB0_125
	v_add_co_u32_e32 v72, vcc, 0x10000, v136
	s_add_u32 m0, s100, 256
	s_nop 0
	global_load_lds_dwordx4 v[136:137], off offset:256
	s_nop 0
	v_addc_co_u32_e32 v73, vcc, 0, v137, vcc
	v_add_co_u32_e32 v80, vcc, 0x20000, v136
	s_nop 1
	v_addc_co_u32_e32 v81, vcc, 0, v137, vcc
	v_add_co_u32_e32 v88, vcc, 0x30000, v136
	s_add_u32 m0, s100, 4352
	s_nop 0
	global_load_lds_dwordx4 v[72:73], off offset:256
	s_nop 0
	s_add_u32 m0, s100, 8448
	s_nop 0
	global_load_lds_dwordx4 v[80:81], off offset:256
	v_addc_co_u32_e32 v89, vcc, 0, v137, vcc
	v_add_co_u32_e32 v96, vcc, 0x400000, v134
	s_add_u32 m0, s100, 12544
	s_nop 0
	global_load_lds_dwordx4 v[88:89], off offset:256
	s_nop 0
	v_addc_co_u32_e32 v97, vcc, 0, v135, vcc
	v_add_co_u32_e32 v104, vcc, 0x410000, v134
	s_nop 1
	v_addc_co_u32_e32 v105, vcc, 0, v135, vcc
	v_add_co_u32_e32 v112, vcc, 0x420000, v134
	s_add_u32 m0, s100, 16640
	s_nop 0
	global_load_lds_dwordx4 v[96:97], off offset:256
	s_nop 0
	s_add_u32 m0, s100, 20736
	s_nop 0
	global_load_lds_dwordx4 v[104:105], off offset:256
	v_addc_co_u32_e32 v113, vcc, 0, v135, vcc
	v_add_co_u32_e32 v120, vcc, 0x430000, v134
	s_nop 1
	v_addc_co_u32_e32 v121, vcc, 0, v135, vcc
	s_add_u32 m0, s100, 24832
	s_nop 0
	global_load_lds_dwordx4 v[112:113], off offset:256
	s_nop 0
	s_add_u32 m0, s100, 28928
	s_nop 0
	global_load_lds_dwordx4 v[120:121], off offset:256
	s_branch .LBB0_125

; #define G_LOAD(RA, RB, k_) do { \
;     _Pragma("unroll") for (int i = 0; i < 4; ++i) RA[i] = *(const u32x4*)&Ap[i * sa + (k_)]; \
;     _Pragma("unroll") for (int i = 0; i < 2 * NJ; ++i) RB[i] = *(const u32x4*)&Bp[i * sbb + (k_)]; } while (0)
; template <int NJ>
; DI void gemm_core(const h16* __restrict__ A, int lda, const h16* __restrict__ Bt, int ldb, int K,
;                   floatx16 (&acc)[2][NJ], h16* As, h16* Bs) {
;     ...
;   G_LOAD(ra0, rb0, 0);
;   if (64 < K) G_LOAD(ra1, rb1, 64);
;   for (int k0 = 0; k0 < K; k0 += 128) {
;     G_STEP(ra0, rb0, k0 + 128);
;     if (k0 + 64 < K) G_STEP(ra1, rb1, k0 + 192);
;   }
; __global__ void __launch_bounds__(256, 2) mega(Params p) {
;     ...
;       if (PH(3)) for (int lj = xj.r; lj < 64 * njt; lj += xj.nrank) {
;         const int mt = xj.x * 64 + lj / njt, jt = ps == 0 ? ((lj + (lj >> 6)) & 7) : 3 + lj % 5, m0 = mt * 128;
;         floatx16 acc[2][2]; acc_zero<2>(acc);
;         if (jt < 3) {
;           gemm_core<2>(x16 + (size_t)m0 * 1024, 1024, Wt + WT_IN + (size_t)(512 + jt * 512 + 128 * ps) * 1024, 1024, 1024, acc, As, Bs);
;           epi_apply<2>(acc, [&](int r, int c, float v) { zpass[(size_t)(m0 + r) * 384 + jt * 128 + c] = (h16)v; });
;         } else if (jt < 5) {
.LBB0_295:
	ds_read_b128 v[142:145], v190 offset:512
	ds_read_b128 v[146:149], v191 offset:512
	ds_read_b128 v[166:169], v190 offset:4608
	ds_read_b128 v[170:173], v191 offset:4608
	ds_read_b128 v[174:177], v194 offset:16896
	ds_read_b128 v[178:181], v195 offset:16896
	ds_read_b128 v[182:185], v194 offset:20992
	ds_read_b128 v[186:189], v195 offset:20992
	s_waitcnt lgkmcnt(3)
	v_mfma_f32_32x32x16_f16 v[48:63], v[142:145], v[174:177], v[48:63]
	s_waitcnt lgkmcnt(1)
	v_mfma_f32_32x32x16_f16 v[32:47], v[142:145], v[182:185], v[32:47]
	v_mfma_f32_32x32x16_f16 v[16:31], v[166:169], v[174:177], v[16:31]
	v_mfma_f32_32x32x16_f16 v[0:15], v[166:169], v[182:185], v[0:15]
	v_add_co_u32_e32 v76, vcc, 0x10000, v136
	s_add_u32 m0, s100, 41856
	s_nop 0
	global_load_lds_dwordx4 v[136:137], off offset:128
	s_nop 0
	v_addc_co_u32_e32 v77, vcc, 0, v137, vcc
	v_add_co_u32_e32 v84, vcc, 0x20000, v136
	s_nop 1
	v_addc_co_u32_e32 v85, vcc, 0, v137, vcc
	v_add_co_u32_e32 v92, vcc, 0x30000, v136
	s_add_u32 m0, s100, 45952
	s_nop 0
	global_load_lds_dwordx4 v[76:77], off offset:128
	s_nop 0
	s_add_u32 m0, s100, 50048
	s_nop 0
	global_load_lds_dwordx4 v[84:85], off offset:128
	ds_read_b128 v[142:145], v192 offset:512
	ds_read_b128 v[166:169], v192 offset:4608
	ds_read_b128 v[174:177], v196 offset:16896
	ds_read_b128 v[182:185], v196 offset:20992
	v_mfma_f32_32x32x16_f16 v[48:63], v[146:149], v[178:181], v[48:63]
	s_waitcnt lgkmcnt(4)
	v_mfma_f32_32x32x16_f16 v[32:47], v[146:149], v[186:189], v[32:47]
	v_mfma_f32_32x32x16_f16 v[16:31], v[170:173], v[178:181], v[16:31]
	v_mfma_f32_32x32x16_f16 v[0:15], v[170:173], v[186:189], v[0:15]
	v_addc_co_u32_e32 v93, vcc, 0, v137, vcc
	v_add_co_u32_e32 v108, vcc, 0x10000, v134
	s_add_u32 m0, s100, 54144
	s_nop 0
	global_load_lds_dwordx4 v[92:93], off offset:128
	s_nop 0
	s_add_u32 m0, s100, 58240
	s_nop 0
	global_load_lds_dwordx4 v[134:135], off offset:128
	v_addc_co_u32_e32 v109, vcc, 0, v135, vcc
	v_add_co_u32_e32 v116, vcc, 0x20000, v134
	s_nop 1
	v_addc_co_u32_e32 v117, vcc, 0, v135, vcc
	v_add_co_u32_e32 v124, vcc, 0x30000, v134
	s_add_u32 m0, s100, 62336
	s_nop 0
	global_load_lds_dwordx4 v[108:109], off offset:128
	ds_read_b128 v[146:149], v193 offset:512
	ds_read_b128 v[170:173], v193 offset:4608
	ds_read_b128 v[178:181], v197 offset:16896
	ds_read_b128 v[186:189], v197 offset:20992
	s_waitcnt lgkmcnt(5)
	v_mfma_f32_32x32x16_f16 v[48:63], v[142:145], v[174:177], v[48:63]
	s_waitcnt lgkmcnt(4)
	v_mfma_f32_32x32x16_f16 v[32:47], v[142:145], v[182:185], v[32:47]
	v_mfma_f32_32x32x16_f16 v[16:31], v[166:169], v[174:177], v[16:31]
	v_mfma_f32_32x32x16_f16 v[0:15], v[166:169], v[182:185], v[0:15]
	s_nop 0
	s_add_u32 m0, s100, 66432
	s_nop 0
	global_load_lds_dwordx4 v[116:117], off offset:128
	v_addc_co_u32_e32 v125, vcc, 0, v135, vcc
	s_add_u32 m0, s100, 70528
	s_nop 0
	global_load_lds_dwordx4 v[124:125], off offset:128
	s_waitcnt lgkmcnt(1)
	v_mfma_f32_32x32x16_f16 v[48:63], v[146:149], v[178:181], v[48:63]
	s_waitcnt lgkmcnt(0)
	v_mfma_f32_32x32x16_f16 v[32:47], v[146:149], v[186:189], v[32:47]
	v_mfma_f32_32x32x16_f16 v[16:31], v[170:173], v[178:181], v[16:31]
	v_mfma_f32_32x32x16_f16 v[0:15], v[170:173], v[186:189], v[0:15]
	s_waitcnt vmcnt(0)
	s_barrier
	s_and_b64 vcc, exec, s[40:41]
	s_cbranch_vccnz .LBB0_292
	v_add_co_u32_e32 v72, vcc, 0x10000, v136
	s_add_u32 m0, s100, 256
	s_nop 0
	global_load_lds_dwordx4 v[136:137], off offset:256
	s_nop 0
	v_addc_co_u32_e32 v73, vcc, 0, v137, vcc
	v_add_co_u32_e32 v80, vcc, 0x20000, v136
	s_nop 1
	v_addc_co_u32_e32 v81, vcc, 0, v137, vcc
	v_add_co_u32_e32 v88, vcc, 0x30000, v136
	s_add_u32 m0, s100, 4352
	s_nop 0
	global_load_lds_dwordx4 v[72:73], off offset:256
	s_nop 0
	s_add_u32 m0, s100, 8448
	s_nop 0
	global_load_lds_dwordx4 v[80:81], off offset:256
	v_addc_co_u32_e32 v89, vcc, 0, v137, vcc
	v_add_co_u32_e32 v104, vcc, s55, v134
	s_add_u32 m0, s100, 12544
	s_nop 0
	global_load_lds_dwordx4 v[88:89], off offset:256
	s_nop 0
	s_add_u32 m0, s100, 16640
	s_nop 0
	global_load_lds_dwordx4 v[134:135], off offset:256
	v_addc_co_u32_e32 v105, vcc, 0, v135, vcc
	v_add_co_u32_e32 v112, vcc, 0x20000, v134
	s_nop 1
	v_addc_co_u32_e32 v113, vcc, 0, v135, vcc
	v_add_co_u32_e32 v120, vcc, 0x30000, v134
	s_add_u32 m0, s100, 20736
	s_nop 0
	global_load_lds_dwordx4 v[104:105], off offset:256
	s_nop 0
	s_add_u32 m0, s100, 24832
	s_nop 0
	global_load_lds_dwordx4 v[112:113], off offset:256
	v_addc_co_u32_e32 v121, vcc, 0, v135, vcc
	s_add_u32 m0, s100, 28928
	s_nop 0
	global_load_lds_dwordx4 v[120:121], off offset:256
	s_branch .LBB0_292

; #define G_LOAD(RA, RB, k_) do { \
;     _Pragma("unroll") for (int i = 0; i < 4; ++i) RA[i] = *(const u32x4*)&Ap[i * sa + (k_)]; \
;     _Pragma("unroll") for (int i = 0; i < 2 * NJ; ++i) RB[i] = *(const u32x4*)&Bp[i * sbb + (k_)]; } while (0)
; template <int NJ>
; DI void gemm_core(const h16* __restrict__ A, int lda, const h16* __restrict__ Bt, int ldb, int K,
;                   floatx16 (&acc)[2][NJ], h16* As, h16* Bs) {
;     ...
;   G_LOAD(ra0, rb0, 0);
;   if (64 < K) G_LOAD(ra1, rb1, 64);
;   for (int k0 = 0; k0 < K; k0 += 128) {
;     G_STEP(ra0, rb0, k0 + 128);
;     if (k0 + 64 < K) G_STEP(ra1, rb1, k0 + 192);
;   }
; __global__ void __launch_bounds__(256, 2) mega(Params p) {
;     ...
;         } else {
;           const int r2 = (blockIdx.x - 72) >> 3, nr2 = (gridDim.x - 72) >> 3;
;           for (int lj = r2; lj < 64 * 3; lj += nr2) {
;             const int mt = xj.x * 64 + lj / 3, jt = lj % 3, m0 = mt * 128;
;             floatx16 acc[2][2]; acc_zero<2>(acc);
;             gemm_core<2>(x16 + (size_t)m0 * 1024, 1024, Wt + WT_IN + (size_t)(512 + jt * 512 + 128 * (ps + 1)) * 1024, 1024, 1024, acc, As, Bs);
;             epi_apply<2>(acc, [&](int r, int c, float v) { zpass[(size_t)(m0 + r) * 384 + jt * 128 + c] = (h16)v; });
;           }
;         }
.LBB0_474:
	ds_read_b128 v[142:145], v190 offset:512
	ds_read_b128 v[146:149], v191 offset:512
	ds_read_b128 v[166:169], v190 offset:4608
	ds_read_b128 v[170:173], v191 offset:4608
	ds_read_b128 v[174:177], v194 offset:16896
	ds_read_b128 v[178:181], v195 offset:16896
	ds_read_b128 v[182:185], v194 offset:20992
	ds_read_b128 v[186:189], v195 offset:20992
	s_waitcnt lgkmcnt(3)
	v_mfma_f32_32x32x16_f16 v[48:63], v[142:145], v[174:177], v[48:63]
	s_waitcnt lgkmcnt(1)
	v_mfma_f32_32x32x16_f16 v[32:47], v[142:145], v[182:185], v[32:47]
	v_mfma_f32_32x32x16_f16 v[16:31], v[166:169], v[174:177], v[16:31]
	v_mfma_f32_32x32x16_f16 v[0:15], v[166:169], v[182:185], v[0:15]
	v_add_co_u32_e32 v76, vcc, 0x10000, v136
	s_add_u32 m0, s100, 41856
	s_nop 0
	global_load_lds_dwordx4 v[136:137], off offset:128
	s_nop 0
	v_addc_co_u32_e32 v77, vcc, 0, v137, vcc
	v_add_co_u32_e32 v84, vcc, 0x20000, v136
	s_nop 1
	v_addc_co_u32_e32 v85, vcc, 0, v137, vcc
	v_add_co_u32_e32 v92, vcc, 0x30000, v136
	s_add_u32 m0, s100, 45952
	s_nop 0
	global_load_lds_dwordx4 v[76:77], off offset:128
	s_nop 0
	s_add_u32 m0, s100, 50048
	s_nop 0
	global_load_lds_dwordx4 v[84:85], off offset:128
	ds_read_b128 v[142:145], v192 offset:512
	ds_read_b128 v[166:169], v192 offset:4608
	ds_read_b128 v[174:177], v196 offset:16896
	ds_read_b128 v[182:185], v196 offset:20992
	v_mfma_f32_32x32x16_f16 v[48:63], v[146:149], v[178:181], v[48:63]
	s_waitcnt lgkmcnt(4)
	v_mfma_f32_32x32x16_f16 v[32:47], v[146:149], v[186:189], v[32:47]
	v_mfma_f32_32x32x16_f16 v[16:31], v[170:173], v[178:181], v[16:31]
	v_mfma_f32_32x32x16_f16 v[0:15], v[170:173], v[186:189], v[0:15]
	v_addc_co_u32_e32 v93, vcc, 0, v137, vcc
	v_add_co_u32_e32 v100, vcc, 0x140000, v134
	s_add_u32 m0, s100, 54144
	s_nop 0
	global_load_lds_dwordx4 v[92:93], off offset:128
	s_nop 0
	v_addc_co_u32_e32 v101, vcc, 0, v135, vcc
	v_add_co_u32_e32 v108, vcc, 0x150000, v134
	s_nop 1
	v_addc_co_u32_e32 v109, vcc, 0, v135, vcc
	v_add_co_u32_e32 v116, vcc, 0x160000, v134
	s_add_u32 m0, s100, 58240
	s_nop 0
	global_load_lds_dwordx4 v[100:101], off offset:128
	s_nop 0
	s_add_u32 m0, s100, 62336
	s_nop 0
	global_load_lds_dwordx4 v[108:109], off offset:128
	ds_read_b128 v[146:149], v193 offset:512
	ds_read_b128 v[170:173], v193 offset:4608
	ds_read_b128 v[178:181], v197 offset:16896
	ds_read_b128 v[186:189], v197 offset:20992
	s_waitcnt lgkmcnt(5)
	v_mfma_f32_32x32x16_f16 v[48:63], v[142:145], v[174:177], v[48:63]
	s_waitcnt lgkmcnt(4)
	v_mfma_f32_32x32x16_f16 v[32:47], v[142:145], v[182:185], v[32:47]
	v_mfma_f32_32x32x16_f16 v[16:31], v[166:169], v[174:177], v[16:31]
	v_mfma_f32_32x32x16_f16 v[0:15], v[166:169], v[182:185], v[0:15]
	v_addc_co_u32_e32 v117, vcc, 0, v135, vcc
	v_add_co_u32_e32 v124, vcc, 0x170000, v134
	s_nop 1
	v_addc_co_u32_e32 v125, vcc, 0, v135, vcc
	s_add_u32 m0, s100, 66432
	s_nop 0
	global_load_lds_dwordx4 v[116:117], off offset:128
	s_nop 0
	s_add_u32 m0, s100, 70528
	s_nop 0
	global_load_lds_dwordx4 v[124:125], off offset:128
	s_waitcnt lgkmcnt(1)
	v_mfma_f32_32x32x16_f16 v[48:63], v[146:149], v[178:181], v[48:63]
	s_waitcnt lgkmcnt(0)
	v_mfma_f32_32x32x16_f16 v[32:47], v[146:149], v[186:189], v[32:47]
	v_mfma_f32_32x32x16_f16 v[16:31], v[170:173], v[178:181], v[16:31]
	v_mfma_f32_32x32x16_f16 v[0:15], v[170:173], v[186:189], v[0:15]
	s_waitcnt vmcnt(0)
	s_barrier
	s_and_b64 vcc, exec, s[42:43]
	s_cbranch_vccnz .LBB0_471
	v_add_co_u32_e32 v72, vcc, 0x10000, v136
	s_add_u32 m0, s100, 256
	s_nop 0
	global_load_lds_dwordx4 v[136:137], off offset:256
	s_nop 0
	v_addc_co_u32_e32 v73, vcc, 0, v137, vcc
	v_add_co_u32_e32 v80, vcc, 0x20000, v136
	s_nop 1
	v_addc_co_u32_e32 v81, vcc, 0, v137, vcc
	v_add_co_u32_e32 v88, vcc, 0x30000, v136
	s_add_u32 m0, s100, 4352
	s_nop 0
	global_load_lds_dwordx4 v[72:73], off offset:256
	s_nop 0
	s_add_u32 m0, s100, 8448
	s_nop 0
	global_load_lds_dwordx4 v[80:81], off offset:256
	v_addc_co_u32_e32 v89, vcc, 0, v137, vcc
	v_add_co_u32_e32 v96, vcc, 0x140000, v134
	s_add_u32 m0, s100, 12544
	s_nop 0
	global_load_lds_dwordx4 v[88:89], off offset:256
	s_nop 0
	v_addc_co_u32_e32 v97, vcc, 0, v135, vcc
	v_add_co_u32_e32 v104, vcc, 0x150000, v134
	s_nop 1
	v_addc_co_u32_e32 v105, vcc, 0, v135, vcc
	v_add_co_u32_e32 v112, vcc, 0x160000, v134
	s_add_u32 m0, s100, 16640
	s_nop 0
	global_load_lds_dwordx4 v[96:97], off offset:256
	s_nop 0
	s_add_u32 m0, s100, 20736
	s_nop 0
	global_load_lds_dwordx4 v[104:105], off offset:256
	v_addc_co_u32_e32 v113, vcc, 0, v135, vcc
	v_add_co_u32_e32 v120, vcc, 0x170000, v134
	s_nop 1
	v_addc_co_u32_e32 v121, vcc, 0, v135, vcc
	s_add_u32 m0, s100, 24832
	s_nop 0
	global_load_lds_dwordx4 v[112:113], off offset:256
	s_nop 0
	s_add_u32 m0, s100, 28928
	s_nop 0
	global_load_lds_dwordx4 v[120:121], off offset:256
	s_branch .LBB0_471

; #define G_LOAD(RA, RB, k_) do { \
;     _Pragma("unroll") for (int i = 0; i < 4; ++i) RA[i] = *(const u32x4*)&Ap[i * sa + (k_)]; \
;     _Pragma("unroll") for (int i = 0; i < 2 * NJ; ++i) RB[i] = *(const u32x4*)&Bp[i * sbb + (k_)]; } while (0)
; template <int NJ>
; DI void gemm_core(const h16* __restrict__ A, int lda, const h16* __restrict__ Bt, int ldb, int K,
;                   floatx16 (&acc)[2][NJ], h16* As, h16* Bs) {
;     ...
;   G_LOAD(ra0, rb0, 0);
;   if (64 < K) G_LOAD(ra1, rb1, 64);
;   for (int k0 = 0; k0 < K; k0 += 128) {
;     G_STEP(ra0, rb0, k0 + 128);
;     if (k0 + 64 < K) G_STEP(ra1, rb1, k0 + 192);
;   }
; __global__ void __launch_bounds__(256, 2) mega(Params p) {
;     ...
;         else if (ps == 3) {
;           const int r2 = (blockIdx.x - 72) >> 3, nr2 = (gridDim.x - 72) >> 3;
;           for (int lj = r2; lj < 64 * 6; lj += nr2) {
;             const int mt = xj.x * 64 + lj / 6, nt = lj % 6, m0 = mt * 128;
;             floatx16 acc[2][2]; acc_zero<2>(acc);
;             gemm_core<2>(x16 + (size_t)m0 * 1024, 1024, Wt + WT_IN + (size_t)(2432 + nt * 128) * 1024, 1024, 1024, acc, As, Bs);
;             epi_apply<2>(acc, [&](int r, int c, float v) { zatt[(size_t)(m0 + r) * 768 + nt * 128 + c] = (h16)v; });
;           }
.LBB0_500:
	ds_read_b128 v[142:145], v190 offset:512
	ds_read_b128 v[146:149], v191 offset:512
	ds_read_b128 v[166:169], v190 offset:4608
	ds_read_b128 v[170:173], v191 offset:4608
	ds_read_b128 v[174:177], v194 offset:16896
	ds_read_b128 v[178:181], v195 offset:16896
	ds_read_b128 v[182:185], v194 offset:20992
	ds_read_b128 v[186:189], v195 offset:20992
	s_waitcnt lgkmcnt(3)
	v_mfma_f32_32x32x16_f16 v[48:63], v[142:145], v[174:177], v[48:63]
	s_waitcnt lgkmcnt(1)
	v_mfma_f32_32x32x16_f16 v[32:47], v[142:145], v[182:185], v[32:47]
	v_mfma_f32_32x32x16_f16 v[16:31], v[166:169], v[174:177], v[16:31]
	v_mfma_f32_32x32x16_f16 v[0:15], v[166:169], v[182:185], v[0:15]
	v_add_co_u32_e32 v76, vcc, 0x10000, v136
	s_add_u32 m0, s100, 41856
	s_nop 0
	global_load_lds_dwordx4 v[136:137], off offset:128
	s_nop 0
	v_addc_co_u32_e32 v77, vcc, 0, v137, vcc
	v_add_co_u32_e32 v84, vcc, 0x20000, v136
	s_nop 1
	v_addc_co_u32_e32 v85, vcc, 0, v137, vcc
	v_add_co_u32_e32 v92, vcc, 0x30000, v136
	s_add_u32 m0, s100, 45952
	s_nop 0
	global_load_lds_dwordx4 v[76:77], off offset:128
	s_nop 0
	s_add_u32 m0, s100, 50048
	s_nop 0
	global_load_lds_dwordx4 v[84:85], off offset:128
	ds_read_b128 v[142:145], v192 offset:512
	ds_read_b128 v[166:169], v192 offset:4608
	ds_read_b128 v[174:177], v196 offset:16896
	ds_read_b128 v[182:185], v196 offset:20992
	v_mfma_f32_32x32x16_f16 v[48:63], v[146:149], v[178:181], v[48:63]
	s_waitcnt lgkmcnt(4)
	v_mfma_f32_32x32x16_f16 v[32:47], v[146:149], v[186:189], v[32:47]
	v_mfma_f32_32x32x16_f16 v[16:31], v[170:173], v[178:181], v[16:31]
	v_mfma_f32_32x32x16_f16 v[0:15], v[170:173], v[186:189], v[0:15]
	v_addc_co_u32_e32 v93, vcc, 0, v137, vcc
	v_add_co_u32_e32 v100, vcc, 0x4c0000, v134
	s_add_u32 m0, s100, 54144
	s_nop 0
	global_load_lds_dwordx4 v[92:93], off offset:128
	s_nop 0
	v_addc_co_u32_e32 v101, vcc, 0, v135, vcc
	v_add_co_u32_e32 v108, vcc, 0x4d0000, v134
	s_nop 1
	v_addc_co_u32_e32 v109, vcc, 0, v135, vcc
	v_add_co_u32_e32 v116, vcc, 0x4e0000, v134
	s_add_u32 m0, s100, 58240
	s_nop 0
	global_load_lds_dwordx4 v[100:101], off offset:128
	s_nop 0
	s_add_u32 m0, s100, 62336
	s_nop 0
	global_load_lds_dwordx4 v[108:109], off offset:128
	ds_read_b128 v[146:149], v193 offset:512
	ds_read_b128 v[170:173], v193 offset:4608
	ds_read_b128 v[178:181], v197 offset:16896
	ds_read_b128 v[186:189], v197 offset:20992
	s_waitcnt lgkmcnt(5)
	v_mfma_f32_32x32x16_f16 v[48:63], v[142:145], v[174:177], v[48:63]
	s_waitcnt lgkmcnt(4)
	v_mfma_f32_32x32x16_f16 v[32:47], v[142:145], v[182:185], v[32:47]
	v_mfma_f32_32x32x16_f16 v[16:31], v[166:169], v[174:177], v[16:31]
	v_mfma_f32_32x32x16_f16 v[0:15], v[166:169], v[182:185], v[0:15]
	v_addc_co_u32_e32 v117, vcc, 0, v135, vcc
	v_add_co_u32_e32 v124, vcc, 0x4f0000, v134
	s_nop 1
	v_addc_co_u32_e32 v125, vcc, 0, v135, vcc
	s_add_u32 m0, s100, 66432
	s_nop 0
	global_load_lds_dwordx4 v[116:117], off offset:128
	s_nop 0
	s_add_u32 m0, s100, 70528
	s_nop 0
	global_load_lds_dwordx4 v[124:125], off offset:128
	s_waitcnt lgkmcnt(1)
	v_mfma_f32_32x32x16_f16 v[48:63], v[146:149], v[178:181], v[48:63]
	s_waitcnt lgkmcnt(0)
	v_mfma_f32_32x32x16_f16 v[32:47], v[146:149], v[186:189], v[32:47]
	v_mfma_f32_32x32x16_f16 v[16:31], v[170:173], v[178:181], v[16:31]
	v_mfma_f32_32x32x16_f16 v[0:15], v[170:173], v[186:189], v[0:15]
	s_waitcnt vmcnt(0)
	s_barrier
	s_and_b64 vcc, exec, s[42:43]
	s_cbranch_vccnz .LBB0_497
	v_add_co_u32_e32 v72, vcc, 0x10000, v136
	s_add_u32 m0, s100, 256
	s_nop 0
	global_load_lds_dwordx4 v[136:137], off offset:256
	s_nop 0
	v_addc_co_u32_e32 v73, vcc, 0, v137, vcc
	v_add_co_u32_e32 v80, vcc, 0x20000, v136
	s_nop 1
	v_addc_co_u32_e32 v81, vcc, 0, v137, vcc
	v_add_co_u32_e32 v88, vcc, 0x30000, v136
	s_add_u32 m0, s100, 4352
	s_nop 0
	global_load_lds_dwordx4 v[72:73], off offset:256
	s_nop 0
	s_add_u32 m0, s100, 8448
	s_nop 0
	global_load_lds_dwordx4 v[80:81], off offset:256
	v_addc_co_u32_e32 v89, vcc, 0, v137, vcc
	v_add_co_u32_e32 v96, vcc, 0x4c0000, v134
	s_add_u32 m0, s100, 12544
	s_nop 0
	global_load_lds_dwordx4 v[88:89], off offset:256
	s_nop 0
	v_addc_co_u32_e32 v97, vcc, 0, v135, vcc
	v_add_co_u32_e32 v104, vcc, 0x4d0000, v134
	s_nop 1
	v_addc_co_u32_e32 v105, vcc, 0, v135, vcc
	v_add_co_u32_e32 v112, vcc, 0x4e0000, v134
	s_add_u32 m0, s100, 16640
	s_nop 0
	global_load_lds_dwordx4 v[96:97], off offset:256
	s_nop 0
	s_add_u32 m0, s100, 20736
	s_nop 0
	global_load_lds_dwordx4 v[104:105], off offset:256
	v_addc_co_u32_e32 v113, vcc, 0, v135, vcc
	v_add_co_u32_e32 v120, vcc, 0x4f0000, v134
	s_nop 1
	v_addc_co_u32_e32 v121, vcc, 0, v135, vcc
	s_add_u32 m0, s100, 24832
	s_nop 0
	global_load_lds_dwordx4 v[112:113], off offset:256
	s_nop 0
	s_add_u32 m0, s100, 28928
	s_nop 0
	global_load_lds_dwordx4 v[120:121], off offset:256
	s_branch .LBB0_497

; #define G_LOAD(RA, RB, k_) do { \
;     _Pragma("unroll") for (int i = 0; i < 4; ++i) RA[i] = *(const u32x4*)&Ap[i * sa + (k_)]; \
;     _Pragma("unroll") for (int i = 0; i < 2 * NJ; ++i) RB[i] = *(const u32x4*)&Bp[i * sbb + (k_)]; } while (0)
; template <int NJ>
; DI void gemm_core(const h16* __restrict__ A, int lda, const h16* __restrict__ Bt, int ldb, int K,
;                   floatx16 (&acc)[2][NJ], h16* As, h16* Bs) {
;     ...
;   G_LOAD(ra0, rb0, 0);
;   if (64 < K) G_LOAD(ra1, rb1, 64);
;   for (int k0 = 0; k0 < K; k0 += 128) {
;     G_STEP(ra0, rb0, k0 + 128);
;     if (k0 + 64 < K) G_STEP(ra1, rb1, k0 + 192);
;   }
; __global__ void __launch_bounds__(256, 2) mega(Params p) {
;     ...
;     if (PH(9)) for (int lj = xj.r; lj < 64 * 4; lj += xj.nrank) {
;       int mt, nt; xjob_map(xj, lj, 512, 4, mt, nt); const int m0 = mt * 128;
;       const int wrow = nt * 128;
;       floatx16 acc[2][2]; acc_zero<2>(acc);
;       gemm_core<2>(x16 + (size_t)m0 * 1024, 1024, Wt + WT_IN + (size_t)wrow * 1024, 1024, 1024, acc, As, Bs);
;       epi_apply<2>(acc, [&](int r, int c, float v) { zpa[(size_t)(m0 + r) * 512 + nt * 128 + c] = (h16)v; });
;     }
.LBB0_676:
	ds_read_b128 v[142:145], v190 offset:512
	ds_read_b128 v[146:149], v191 offset:512
	ds_read_b128 v[166:169], v190 offset:4608
	ds_read_b128 v[170:173], v191 offset:4608
	ds_read_b128 v[174:177], v194 offset:16896
	ds_read_b128 v[178:181], v195 offset:16896
	ds_read_b128 v[182:185], v194 offset:20992
	ds_read_b128 v[186:189], v195 offset:20992
	s_waitcnt lgkmcnt(3)
	v_mfma_f32_32x32x16_f16 v[48:63], v[142:145], v[174:177], v[48:63]
	s_waitcnt lgkmcnt(1)
	v_mfma_f32_32x32x16_f16 v[32:47], v[142:145], v[182:185], v[32:47]
	v_mfma_f32_32x32x16_f16 v[16:31], v[166:169], v[174:177], v[16:31]
	v_mfma_f32_32x32x16_f16 v[0:15], v[166:169], v[182:185], v[0:15]
	v_add_co_u32_e32 v76, vcc, 0x10000, v136
	s_add_u32 m0, s100, 41856
	s_nop 0
	global_load_lds_dwordx4 v[136:137], off offset:128
	s_nop 0
	v_addc_co_u32_e32 v77, vcc, 0, v137, vcc
	v_add_co_u32_e32 v84, vcc, 0x20000, v136
	s_nop 1
	v_addc_co_u32_e32 v85, vcc, 0, v137, vcc
	v_add_co_u32_e32 v92, vcc, 0x30000, v136
	s_add_u32 m0, s100, 45952
	s_nop 0
	global_load_lds_dwordx4 v[76:77], off offset:128
	s_nop 0
	s_add_u32 m0, s100, 50048
	s_nop 0
	global_load_lds_dwordx4 v[84:85], off offset:128
	ds_read_b128 v[142:145], v192 offset:512
	ds_read_b128 v[166:169], v192 offset:4608
	ds_read_b128 v[174:177], v196 offset:16896
	ds_read_b128 v[182:185], v196 offset:20992
	v_mfma_f32_32x32x16_f16 v[48:63], v[146:149], v[178:181], v[48:63]
	s_waitcnt lgkmcnt(4)
	v_mfma_f32_32x32x16_f16 v[32:47], v[146:149], v[186:189], v[32:47]
	v_mfma_f32_32x32x16_f16 v[16:31], v[170:173], v[178:181], v[16:31]
	v_mfma_f32_32x32x16_f16 v[0:15], v[170:173], v[186:189], v[0:15]
	v_addc_co_u32_e32 v93, vcc, 0, v137, vcc
	v_add_co_u32_e32 v108, vcc, 0x10000, v134
	s_add_u32 m0, s100, 54144
	s_nop 0
	global_load_lds_dwordx4 v[92:93], off offset:128
	s_nop 0
	s_add_u32 m0, s100, 58240
	s_nop 0
	global_load_lds_dwordx4 v[134:135], off offset:128
	v_addc_co_u32_e32 v109, vcc, 0, v135, vcc
	v_add_co_u32_e32 v116, vcc, 0x20000, v134
	s_nop 1
	v_addc_co_u32_e32 v117, vcc, 0, v135, vcc
	v_add_co_u32_e32 v124, vcc, 0x30000, v134
	s_add_u32 m0, s100, 62336
	s_nop 0
	global_load_lds_dwordx4 v[108:109], off offset:128
	ds_read_b128 v[146:149], v193 offset:512
	ds_read_b128 v[170:173], v193 offset:4608
	ds_read_b128 v[178:181], v197 offset:16896
	ds_read_b128 v[186:189], v197 offset:20992
	s_waitcnt lgkmcnt(5)
	v_mfma_f32_32x32x16_f16 v[48:63], v[142:145], v[174:177], v[48:63]
	s_waitcnt lgkmcnt(4)
	v_mfma_f32_32x32x16_f16 v[32:47], v[142:145], v[182:185], v[32:47]
	v_mfma_f32_32x32x16_f16 v[16:31], v[166:169], v[174:177], v[16:31]
	v_mfma_f32_32x32x16_f16 v[0:15], v[166:169], v[182:185], v[0:15]
	s_nop 0
	s_add_u32 m0, s100, 66432
	s_nop 0
	global_load_lds_dwordx4 v[116:117], off offset:128
	v_addc_co_u32_e32 v125, vcc, 0, v135, vcc
	s_add_u32 m0, s100, 70528
	s_nop 0
	global_load_lds_dwordx4 v[124:125], off offset:128
	s_waitcnt lgkmcnt(1)
	v_mfma_f32_32x32x16_f16 v[48:63], v[146:149], v[178:181], v[48:63]
	s_waitcnt lgkmcnt(0)
	v_mfma_f32_32x32x16_f16 v[32:47], v[146:149], v[186:189], v[32:47]
	v_mfma_f32_32x32x16_f16 v[16:31], v[170:173], v[178:181], v[16:31]
	v_mfma_f32_32x32x16_f16 v[0:15], v[170:173], v[186:189], v[0:15]
	s_waitcnt vmcnt(0)
	s_barrier
	s_and_b64 vcc, exec, s[44:45]
	s_cbranch_vccnz .LBB0_673
	v_add_co_u32_e32 v72, vcc, 0x10000, v136
	s_add_u32 m0, s100, 256
	s_nop 0
	global_load_lds_dwordx4 v[136:137], off offset:256
	s_nop 0
	v_addc_co_u32_e32 v73, vcc, 0, v137, vcc
	v_add_co_u32_e32 v80, vcc, 0x20000, v136
	s_nop 1
	v_addc_co_u32_e32 v81, vcc, 0, v137, vcc
	v_add_co_u32_e32 v88, vcc, 0x30000, v136
	s_add_u32 m0, s100, 4352
	s_nop 0
	global_load_lds_dwordx4 v[72:73], off offset:256
	s_nop 0
	s_add_u32 m0, s100, 8448
	s_nop 0
	global_load_lds_dwordx4 v[80:81], off offset:256
	v_addc_co_u32_e32 v89, vcc, 0, v137, vcc
	v_add_co_u32_e32 v104, vcc, s55, v134
	s_add_u32 m0, s100, 12544
	s_nop 0
	global_load_lds_dwordx4 v[88:89], off offset:256
	s_nop 0
	s_add_u32 m0, s100, 16640
	s_nop 0
	global_load_lds_dwordx4 v[134:135], off offset:256
	v_addc_co_u32_e32 v105, vcc, 0, v135, vcc
	v_add_co_u32_e32 v112, vcc, 0x20000, v134
	s_nop 1
	v_addc_co_u32_e32 v113, vcc, 0, v135, vcc
	v_add_co_u32_e32 v120, vcc, 0x30000, v134
	s_add_u32 m0, s100, 20736
	s_nop 0
	global_load_lds_dwordx4 v[104:105], off offset:256
	s_nop 0
	s_add_u32 m0, s100, 24832
	s_nop 0
	global_load_lds_dwordx4 v[112:113], off offset:256
	v_addc_co_u32_e32 v121, vcc, 0, v135, vcc
	s_add_u32 m0, s100, 28928
	s_nop 0
	global_load_lds_dwordx4 v[120:121], off offset:256
	s_branch .LBB0_673

; #define G_LOAD(RA, RB, k_) do { \
;     _Pragma("unroll") for (int i = 0; i < 4; ++i) RA[i] = *(const u32x4*)&Ap[i * sa + (k_)]; \
;     _Pragma("unroll") for (int i = 0; i < 2 * NJ; ++i) RB[i] = *(const u32x4*)&Bp[i * sbb + (k_)]; } while (0)
; template <int NJ>
; DI void gemm_core(const h16* __restrict__ A, int lda, const h16* __restrict__ Bt, int ldb, int K,
;                   floatx16 (&acc)[2][NJ], h16* As, h16* Bs) {
;     ...
;   G_LOAD(ra0, rb0, 0);
;   if (64 < K) G_LOAD(ra1, rb1, 64);
;   for (int k0 = 0; k0 < K; k0 += 128) {
;     G_STEP(ra0, rb0, k0 + 128);
;     if (k0 + 64 < K) G_STEP(ra1, rb1, k0 + 192);
;   }
; __global__ void __launch_bounds__(256, 2) mega(Params p) {
;     ...
;     if (PH(14)) for (int lj = xj.r; lj < 64 * 8; lj += xj.nrank) {
;       int mt, nt; xjob_map(xj, lj, 512, 8, mt, nt); const int m0 = mt * 128, n0 = nt * 128;
;       floatx16 acc[2][2]; acc_init_resid<2>(acc, x16 + (size_t)m0 * 1024 + n0, 1024);
;       gemm_core<2>(merged + (size_t)m0 * 1024, 1024, Wt + WT_O + (size_t)n0 * 1024, 1024, 1024, acc, As, Bs);
;       epi_apply<2>(acc, [&](int r, int c, float v) { ypre1[(size_t)(m0 + r) * 1024 + n0 + c] = (h16)v; });
;     }
.LBB0_1047:
	ds_read_b128 v[142:145], v190 offset:512
	ds_read_b128 v[146:149], v191 offset:512
	ds_read_b128 v[166:169], v190 offset:4608
	ds_read_b128 v[170:173], v191 offset:4608
	ds_read_b128 v[174:177], v194 offset:16896
	ds_read_b128 v[178:181], v195 offset:16896
	ds_read_b128 v[182:185], v194 offset:20992
	ds_read_b128 v[186:189], v195 offset:20992
	s_waitcnt lgkmcnt(3)
	v_mfma_f32_32x32x16_f16 v[16:31], v[142:145], v[174:177], v[16:31]
	s_waitcnt lgkmcnt(1)
	v_mfma_f32_32x32x16_f16 v[48:63], v[142:145], v[182:185], v[48:63]
	v_mfma_f32_32x32x16_f16 v[0:15], v[166:169], v[174:177], v[0:15]
	v_mfma_f32_32x32x16_f16 v[32:47], v[166:169], v[182:185], v[32:47]
	v_add_co_u32_e32 v68, vcc, 0x2400000, v136
	s_nop 1
	v_addc_co_u32_e32 v69, vcc, 0, v137, vcc
	v_add_co_u32_e32 v76, vcc, 0x2410000, v136
	s_nop 1
	v_addc_co_u32_e32 v77, vcc, 0, v137, vcc
	v_add_co_u32_e32 v84, vcc, 0x2420000, v136
	s_add_u32 m0, s100, 41856
	s_nop 0
	global_load_lds_dwordx4 v[68:69], off offset:128
	s_nop 0
	s_add_u32 m0, s100, 45952
	s_nop 0
	global_load_lds_dwordx4 v[76:77], off offset:128
	v_addc_co_u32_e32 v85, vcc, 0, v137, vcc
	v_add_co_u32_e32 v92, vcc, 0x2430000, v136
	s_nop 1
	v_addc_co_u32_e32 v93, vcc, 0, v137, vcc
	v_add_co_u32_e32 v100, vcc, 0xf40000, v134
	s_add_u32 m0, s100, 50048
	s_nop 0
	global_load_lds_dwordx4 v[84:85], off offset:128
	ds_read_b128 v[142:145], v192 offset:512
	ds_read_b128 v[166:169], v192 offset:4608
	ds_read_b128 v[174:177], v196 offset:16896
	ds_read_b128 v[182:185], v196 offset:20992
	v_mfma_f32_32x32x16_f16 v[16:31], v[146:149], v[178:181], v[16:31]
	s_waitcnt lgkmcnt(4)
	v_mfma_f32_32x32x16_f16 v[48:63], v[146:149], v[186:189], v[48:63]
	v_mfma_f32_32x32x16_f16 v[0:15], v[170:173], v[178:181], v[0:15]
	v_mfma_f32_32x32x16_f16 v[32:47], v[170:173], v[186:189], v[32:47]
	s_nop 0
	s_add_u32 m0, s100, 54144
	s_nop 0
	global_load_lds_dwordx4 v[92:93], off offset:128
	v_addc_co_u32_e32 v101, vcc, 0, v135, vcc
	v_add_co_u32_e32 v108, vcc, 0xf50000, v134
	s_nop 1
	v_addc_co_u32_e32 v109, vcc, 0, v135, vcc
	v_add_co_u32_e32 v116, vcc, 0xf60000, v134
	s_add_u32 m0, s100, 58240
	s_nop 0
	global_load_lds_dwordx4 v[100:101], off offset:128
	s_nop 0
	s_add_u32 m0, s100, 62336
	s_nop 0
	global_load_lds_dwordx4 v[108:109], off offset:128
	ds_read_b128 v[146:149], v193 offset:512
	ds_read_b128 v[170:173], v193 offset:4608
	ds_read_b128 v[178:181], v197 offset:16896
	ds_read_b128 v[186:189], v197 offset:20992
	s_waitcnt lgkmcnt(5)
	v_mfma_f32_32x32x16_f16 v[16:31], v[142:145], v[174:177], v[16:31]
	s_waitcnt lgkmcnt(4)
	v_mfma_f32_32x32x16_f16 v[48:63], v[142:145], v[182:185], v[48:63]
	v_mfma_f32_32x32x16_f16 v[0:15], v[166:169], v[174:177], v[0:15]
	v_mfma_f32_32x32x16_f16 v[32:47], v[166:169], v[182:185], v[32:47]
	v_addc_co_u32_e32 v117, vcc, 0, v135, vcc
	v_add_co_u32_e32 v124, vcc, 0xf70000, v134
	s_nop 1
	v_addc_co_u32_e32 v125, vcc, 0, v135, vcc
	s_add_u32 m0, s100, 66432
	s_nop 0
	global_load_lds_dwordx4 v[116:117], off offset:128
	s_nop 0
	s_add_u32 m0, s100, 70528
	s_nop 0
	global_load_lds_dwordx4 v[124:125], off offset:128
	s_waitcnt lgkmcnt(1)
	v_mfma_f32_32x32x16_f16 v[16:31], v[146:149], v[178:181], v[16:31]
	s_waitcnt lgkmcnt(0)
	v_mfma_f32_32x32x16_f16 v[48:63], v[146:149], v[186:189], v[48:63]
	v_mfma_f32_32x32x16_f16 v[0:15], v[170:173], v[178:181], v[0:15]
	v_mfma_f32_32x32x16_f16 v[32:47], v[170:173], v[186:189], v[32:47]
	s_waitcnt vmcnt(0)
	s_barrier
	s_and_b64 vcc, exec, s[44:45]
	s_cbranch_vccnz .LBB0_1044
	v_add_co_u32_e32 v64, vcc, 0x2400000, v136
	s_nop 1
	v_addc_co_u32_e32 v65, vcc, 0, v137, vcc
	v_add_co_u32_e32 v72, vcc, 0x2410000, v136
	s_nop 1
	v_addc_co_u32_e32 v73, vcc, 0, v137, vcc
	v_add_co_u32_e32 v80, vcc, 0x2420000, v136
	s_add_u32 m0, s100, 256
	s_nop 0
	global_load_lds_dwordx4 v[64:65], off offset:256
	s_nop 0
	s_add_u32 m0, s100, 4352
	s_nop 0
	global_load_lds_dwordx4 v[72:73], off offset:256
	v_addc_co_u32_e32 v81, vcc, 0, v137, vcc
	v_add_co_u32_e32 v88, vcc, 0x2430000, v136
	s_nop 1
	v_addc_co_u32_e32 v89, vcc, 0, v137, vcc
	v_add_co_u32_e32 v96, vcc, 0xf40000, v134
	s_add_u32 m0, s100, 8448
	s_nop 0
	global_load_lds_dwordx4 v[80:81], off offset:256
	s_nop 0
	s_add_u32 m0, s100, 12544
	s_nop 0
	global_load_lds_dwordx4 v[88:89], off offset:256
	v_addc_co_u32_e32 v97, vcc, 0, v135, vcc
	v_add_co_u32_e32 v104, vcc, 0xf50000, v134
	s_nop 1
	v_addc_co_u32_e32 v105, vcc, 0, v135, vcc
	v_add_co_u32_e32 v112, vcc, 0xf60000, v134
	s_add_u32 m0, s100, 16640
	s_nop 0
	global_load_lds_dwordx4 v[96:97], off offset:256
	s_nop 0
	s_add_u32 m0, s100, 20736
	s_nop 0
	global_load_lds_dwordx4 v[104:105], off offset:256
	v_addc_co_u32_e32 v113, vcc, 0, v135, vcc
	v_add_co_u32_e32 v120, vcc, 0xf70000, v134
	s_nop 1
	v_addc_co_u32_e32 v121, vcc, 0, v135, vcc
	s_add_u32 m0, s100, 24832
	s_nop 0
	global_load_lds_dwordx4 v[112:113], off offset:256
	s_nop 0
	s_add_u32 m0, s100, 28928
	s_nop 0
	global_load_lds_dwordx4 v[120:121], off offset:256
	s_branch .LBB0_1044

; #define G_LOAD(RA, RB, k_) do { \
;     _Pragma("unroll") for (int i = 0; i < 4; ++i) RA[i] = *(const u32x4*)&Ap[i * sa + (k_)]; \
;     _Pragma("unroll") for (int i = 0; i < 2 * NJ; ++i) RB[i] = *(const u32x4*)&Bp[i * sbb + (k_)]; } while (0)
; template <int NJ>
; DI void gemm_core(const h16* __restrict__ A, int lda, const h16* __restrict__ Bt, int ldb, int K,
;                   floatx16 (&acc)[2][NJ], h16* As, h16* Bs) {
;     ...
;   G_LOAD(ra0, rb0, 0);
;   if (64 < K) G_LOAD(ra1, rb1, 64);
;   for (int k0 = 0; k0 < K; k0 += 128) {
;     G_STEP(ra0, rb0, k0 + 128);
;     if (k0 + 64 < K) G_STEP(ra1, rb1, k0 + 192);
;   }
; __global__ void __launch_bounds__(256, 2) mega(Params p) {
;     ...
;       if (PH(16)) for (int lj = xj.r; lj < 16 * 32; lj += xj.nrank) {
;         int mt, nt; xjob_map(xj, lj, 128, 32, mt, nt); const int m0 = mt * 128, n0 = nt * 128;
;         floatx16 acc[2][2]; acc_zero<2>(acc);
;         gemm_core<2>(x16 + (size_t)(hf * 16384 + m0) * 1024, 1024, Wt + WT_F1 + (size_t)n0 * 1024, 1024, 1024, acc, As, Bs);
;         epi_apply<2>(acc, [&](int r, int c, float v) {
;           const float u = fmaxf(v, 0.f);
;           hid[(size_t)(m0 + r) * 4096 + n0 + c] = (h16)(u * u);
;         });
;       }
.LBB0_1164:
	ds_read_b128 v[142:145], v190 offset:512
	ds_read_b128 v[146:149], v191 offset:512
	ds_read_b128 v[166:169], v190 offset:4608
	ds_read_b128 v[170:173], v191 offset:4608
	ds_read_b128 v[174:177], v194 offset:16896
	ds_read_b128 v[178:181], v195 offset:16896
	ds_read_b128 v[182:185], v194 offset:20992
	ds_read_b128 v[186:189], v195 offset:20992
	s_waitcnt lgkmcnt(3)
	v_mfma_f32_32x32x16_f16 v[48:63], v[142:145], v[174:177], v[48:63]
	s_waitcnt lgkmcnt(1)
	v_mfma_f32_32x32x16_f16 v[32:47], v[142:145], v[182:185], v[32:47]
	v_mfma_f32_32x32x16_f16 v[16:31], v[166:169], v[174:177], v[16:31]
	v_mfma_f32_32x32x16_f16 v[0:15], v[166:169], v[182:185], v[0:15]
	v_add_co_u32_e32 v76, vcc, 0x10000, v136
	s_add_u32 m0, s100, 41856
	s_nop 0
	global_load_lds_dwordx4 v[136:137], off offset:128
	s_nop 0
	v_addc_co_u32_e32 v77, vcc, 0, v137, vcc
	v_add_co_u32_e32 v84, vcc, 0x20000, v136
	s_nop 1
	v_addc_co_u32_e32 v85, vcc, 0, v137, vcc
	v_add_co_u32_e32 v92, vcc, 0x30000, v136
	s_add_u32 m0, s100, 45952
	s_nop 0
	global_load_lds_dwordx4 v[76:77], off offset:128
	s_nop 0
	s_add_u32 m0, s100, 50048
	s_nop 0
	global_load_lds_dwordx4 v[84:85], off offset:128
	ds_read_b128 v[142:145], v192 offset:512
	ds_read_b128 v[166:169], v192 offset:4608
	ds_read_b128 v[174:177], v196 offset:16896
	ds_read_b128 v[182:185], v196 offset:20992
	v_mfma_f32_32x32x16_f16 v[48:63], v[146:149], v[178:181], v[48:63]
	s_waitcnt lgkmcnt(4)
	v_mfma_f32_32x32x16_f16 v[32:47], v[146:149], v[186:189], v[32:47]
	v_mfma_f32_32x32x16_f16 v[16:31], v[170:173], v[178:181], v[16:31]
	v_mfma_f32_32x32x16_f16 v[0:15], v[170:173], v[186:189], v[0:15]
	v_addc_co_u32_e32 v93, vcc, 0, v137, vcc
	v_add_co_u32_e32 v100, vcc, 0x1140000, v134
	s_add_u32 m0, s100, 54144
	s_nop 0
	global_load_lds_dwordx4 v[92:93], off offset:128
	s_nop 0
	v_addc_co_u32_e32 v101, vcc, 0, v135, vcc
	v_add_co_u32_e32 v108, vcc, 0x1150000, v134
	s_nop 1
	v_addc_co_u32_e32 v109, vcc, 0, v135, vcc
	v_add_co_u32_e32 v116, vcc, 0x1160000, v134
	s_add_u32 m0, s100, 58240
	s_nop 0
	global_load_lds_dwordx4 v[100:101], off offset:128
	s_nop 0
	s_add_u32 m0, s100, 62336
	s_nop 0
	global_load_lds_dwordx4 v[108:109], off offset:128
	ds_read_b128 v[146:149], v193 offset:512
	ds_read_b128 v[170:173], v193 offset:4608
	ds_read_b128 v[178:181], v197 offset:16896
	ds_read_b128 v[186:189], v197 offset:20992
	s_waitcnt lgkmcnt(5)
	v_mfma_f32_32x32x16_f16 v[48:63], v[142:145], v[174:177], v[48:63]
	s_waitcnt lgkmcnt(4)
	v_mfma_f32_32x32x16_f16 v[32:47], v[142:145], v[182:185], v[32:47]
	v_mfma_f32_32x32x16_f16 v[16:31], v[166:169], v[174:177], v[16:31]
	v_mfma_f32_32x32x16_f16 v[0:15], v[166:169], v[182:185], v[0:15]
	v_addc_co_u32_e32 v117, vcc, 0, v135, vcc
	v_add_co_u32_e32 v124, vcc, 0x1170000, v134
	s_nop 1
	v_addc_co_u32_e32 v125, vcc, 0, v135, vcc
	s_add_u32 m0, s100, 66432
	s_nop 0
	global_load_lds_dwordx4 v[116:117], off offset:128
	s_nop 0
	s_add_u32 m0, s100, 70528
	s_nop 0
	global_load_lds_dwordx4 v[124:125], off offset:128
	s_waitcnt lgkmcnt(1)
	v_mfma_f32_32x32x16_f16 v[48:63], v[146:149], v[178:181], v[48:63]
	s_waitcnt lgkmcnt(0)
	v_mfma_f32_32x32x16_f16 v[32:47], v[146:149], v[186:189], v[32:47]
	v_mfma_f32_32x32x16_f16 v[16:31], v[170:173], v[178:181], v[16:31]
	v_mfma_f32_32x32x16_f16 v[0:15], v[170:173], v[186:189], v[0:15]
	s_waitcnt vmcnt(0)
	s_barrier
	s_and_b64 vcc, exec, s[46:47]
	s_cbranch_vccnz .LBB0_1161
	v_add_co_u32_e32 v72, vcc, 0x10000, v136
	s_add_u32 m0, s100, 256
	s_nop 0
	global_load_lds_dwordx4 v[136:137], off offset:256
	s_nop 0
	v_addc_co_u32_e32 v73, vcc, 0, v137, vcc
	v_add_co_u32_e32 v80, vcc, 0x20000, v136
	s_nop 1
	v_addc_co_u32_e32 v81, vcc, 0, v137, vcc
	v_add_co_u32_e32 v88, vcc, 0x30000, v136
	s_add_u32 m0, s100, 4352
	s_nop 0
	global_load_lds_dwordx4 v[72:73], off offset:256
	s_nop 0
	s_add_u32 m0, s100, 8448
	s_nop 0
	global_load_lds_dwordx4 v[80:81], off offset:256
	v_addc_co_u32_e32 v89, vcc, 0, v137, vcc
	v_add_co_u32_e32 v96, vcc, 0x1140000, v134
	s_add_u32 m0, s100, 12544
	s_nop 0
	global_load_lds_dwordx4 v[88:89], off offset:256
	s_nop 0
	v_addc_co_u32_e32 v97, vcc, 0, v135, vcc
	v_add_co_u32_e32 v104, vcc, 0x1150000, v134
	s_nop 1
	v_addc_co_u32_e32 v105, vcc, 0, v135, vcc
	v_add_co_u32_e32 v112, vcc, 0x1160000, v134
	s_add_u32 m0, s100, 16640
	s_nop 0
	global_load_lds_dwordx4 v[96:97], off offset:256
	s_nop 0
	s_add_u32 m0, s100, 20736
	s_nop 0
	global_load_lds_dwordx4 v[104:105], off offset:256
	v_addc_co_u32_e32 v113, vcc, 0, v135, vcc
	v_add_co_u32_e32 v120, vcc, 0x1170000, v134
	s_nop 1
	v_addc_co_u32_e32 v121, vcc, 0, v135, vcc
	s_add_u32 m0, s100, 24832
	s_nop 0
	global_load_lds_dwordx4 v[112:113], off offset:256
	s_nop 0
	s_add_u32 m0, s100, 28928
	s_nop 0
	global_load_lds_dwordx4 v[120:121], off offset:256
	s_branch .LBB0_1161

; #define G_LOAD(RA, RB, k_) do { \
;     _Pragma("unroll") for (int i = 0; i < 4; ++i) RA[i] = *(const u32x4*)&Ap[i * sa + (k_)]; \
;     _Pragma("unroll") for (int i = 0; i < 2 * NJ; ++i) RB[i] = *(const u32x4*)&Bp[i * sbb + (k_)]; } while (0)
; template <int NJ>
; DI void gemm_core(const h16* __restrict__ A, int lda, const h16* __restrict__ Bt, int ldb, int K,
;                   floatx16 (&acc)[2][NJ], h16* As, h16* Bs) {
;     ...
;   G_LOAD(ra0, rb0, 0);
;   if (64 < K) G_LOAD(ra1, rb1, 64);
;   for (int k0 = 0; k0 < K; k0 += 128) {
;     G_STEP(ra0, rb0, k0 + 128);
;     if (k0 + 64 < K) G_STEP(ra1, rb1, k0 + 192);
;   }
; __global__ void __launch_bounds__(256, 2) mega(Params p) {
;     ...
;       if (PH(17)) for (int lj = xj.r; lj < 16 * 8; lj += xj.nrank) {
;         int mt, nt; xjob_map(xj, lj, 128, 8, mt, nt); const int m0 = mt * 128, n0 = nt * 128;
;         floatx16 acc[2][2]; acc_init_resid<2>(acc, x16 + (size_t)(hf * 16384 + m0) * 1024 + n0, 1024);
;         gemm_core<2>(hid + (size_t)m0 * 4096, 4096, Wt + WT_F2 + (size_t)n0 * 4096, 4096, 4096, acc, As, Bs);
;         epi_apply<2>(acc, [&](int r, int c, float v) { ypre2[(size_t)(hf * 16384 + m0 + r) * 1024 + n0 + c] = (h16)v; });
;       }
.LBB0_1225:
	ds_read_b128 v[142:145], v190 offset:512
	ds_read_b128 v[146:149], v191 offset:512
	ds_read_b128 v[166:169], v190 offset:4608
	ds_read_b128 v[170:173], v191 offset:4608
	ds_read_b128 v[174:177], v194 offset:16896
	ds_read_b128 v[178:181], v195 offset:16896
	ds_read_b128 v[182:185], v194 offset:20992
	ds_read_b128 v[186:189], v195 offset:20992
	s_waitcnt lgkmcnt(3)
	v_mfma_f32_32x32x16_f16 v[16:31], v[142:145], v[174:177], v[16:31]
	s_waitcnt lgkmcnt(1)
	v_mfma_f32_32x32x16_f16 v[48:63], v[142:145], v[182:185], v[48:63]
	v_mfma_f32_32x32x16_f16 v[0:15], v[166:169], v[174:177], v[0:15]
	v_mfma_f32_32x32x16_f16 v[32:47], v[166:169], v[182:185], v[32:47]
	v_add_co_u32_e32 v68, vcc, 0x2400000, v136
	s_nop 1
	v_addc_co_u32_e32 v69, vcc, 0, v137, vcc
	v_add_co_u32_e32 v76, vcc, 0x2440000, v136
	s_nop 1
	v_addc_co_u32_e32 v77, vcc, 0, v137, vcc
	v_add_co_u32_e32 v84, vcc, 0x2480000, v136
	s_add_u32 m0, s100, 41856
	s_nop 0
	global_load_lds_dwordx4 v[68:69], off offset:128
	s_nop 0
	s_add_u32 m0, s100, 45952
	s_nop 0
	global_load_lds_dwordx4 v[76:77], off offset:128
	v_addc_co_u32_e32 v85, vcc, 0, v137, vcc
	v_add_co_u32_e32 v92, vcc, 0x24c0000, v136
	s_nop 1
	v_addc_co_u32_e32 v93, vcc, 0, v137, vcc
	v_add_co_u32_e32 v100, vcc, 0x1940000, v134
	s_add_u32 m0, s100, 50048
	s_nop 0
	global_load_lds_dwordx4 v[84:85], off offset:128
	ds_read_b128 v[142:145], v192 offset:512
	ds_read_b128 v[166:169], v192 offset:4608
	ds_read_b128 v[174:177], v196 offset:16896
	ds_read_b128 v[182:185], v196 offset:20992
	v_mfma_f32_32x32x16_f16 v[16:31], v[146:149], v[178:181], v[16:31]
	s_waitcnt lgkmcnt(4)
	v_mfma_f32_32x32x16_f16 v[48:63], v[146:149], v[186:189], v[48:63]
	v_mfma_f32_32x32x16_f16 v[0:15], v[170:173], v[178:181], v[0:15]
	v_mfma_f32_32x32x16_f16 v[32:47], v[170:173], v[186:189], v[32:47]
	s_nop 0
	s_add_u32 m0, s100, 54144
	s_nop 0
	global_load_lds_dwordx4 v[92:93], off offset:128
	v_addc_co_u32_e32 v101, vcc, 0, v135, vcc
	v_add_co_u32_e32 v108, vcc, 0x1980000, v134
	s_nop 1
	v_addc_co_u32_e32 v109, vcc, 0, v135, vcc
	v_add_co_u32_e32 v116, vcc, 0x19c0000, v134
	s_add_u32 m0, s100, 58240
	s_nop 0
	global_load_lds_dwordx4 v[100:101], off offset:128
	s_nop 0
	s_add_u32 m0, s100, 62336
	s_nop 0
	global_load_lds_dwordx4 v[108:109], off offset:128
	ds_read_b128 v[146:149], v193 offset:512
	ds_read_b128 v[170:173], v193 offset:4608
	ds_read_b128 v[178:181], v197 offset:16896
	ds_read_b128 v[186:189], v197 offset:20992
	s_waitcnt lgkmcnt(5)
	v_mfma_f32_32x32x16_f16 v[16:31], v[142:145], v[174:177], v[16:31]
	s_waitcnt lgkmcnt(4)
	v_mfma_f32_32x32x16_f16 v[48:63], v[142:145], v[182:185], v[48:63]
	v_mfma_f32_32x32x16_f16 v[0:15], v[166:169], v[174:177], v[0:15]
	v_mfma_f32_32x32x16_f16 v[32:47], v[166:169], v[182:185], v[32:47]
	v_addc_co_u32_e32 v117, vcc, 0, v135, vcc
	v_add_co_u32_e32 v124, vcc, 0x1a00000, v134
	s_nop 1
	v_addc_co_u32_e32 v125, vcc, 0, v135, vcc
	s_add_u32 m0, s100, 66432
	s_nop 0
	global_load_lds_dwordx4 v[116:117], off offset:128
	s_nop 0
	s_add_u32 m0, s100, 70528
	s_nop 0
	global_load_lds_dwordx4 v[124:125], off offset:128
	s_waitcnt lgkmcnt(1)
	v_mfma_f32_32x32x16_f16 v[16:31], v[146:149], v[178:181], v[16:31]
	s_waitcnt lgkmcnt(0)
	v_mfma_f32_32x32x16_f16 v[48:63], v[146:149], v[186:189], v[48:63]
	v_mfma_f32_32x32x16_f16 v[0:15], v[170:173], v[178:181], v[0:15]
	v_mfma_f32_32x32x16_f16 v[32:47], v[170:173], v[186:189], v[32:47]
	s_waitcnt vmcnt(0)
	s_barrier
	s_and_b64 vcc, exec, s[46:47]
	s_cbranch_vccnz .LBB0_1222
	v_add_co_u32_e32 v64, vcc, 0x2400000, v136
	s_nop 1
	v_addc_co_u32_e32 v65, vcc, 0, v137, vcc
	v_add_co_u32_e32 v72, vcc, 0x2440000, v136
	s_nop 1
	v_addc_co_u32_e32 v73, vcc, 0, v137, vcc
	v_add_co_u32_e32 v80, vcc, 0x2480000, v136
	s_add_u32 m0, s100, 256
	s_nop 0
	global_load_lds_dwordx4 v[64:65], off offset:256
	s_nop 0
	s_add_u32 m0, s100, 4352
	s_nop 0
	global_load_lds_dwordx4 v[72:73], off offset:256
	v_addc_co_u32_e32 v81, vcc, 0, v137, vcc
	v_add_co_u32_e32 v88, vcc, 0x24c0000, v136
	s_nop 1
	v_addc_co_u32_e32 v89, vcc, 0, v137, vcc
	v_add_co_u32_e32 v96, vcc, 0x1940000, v134
	s_add_u32 m0, s100, 8448
	s_nop 0
	global_load_lds_dwordx4 v[80:81], off offset:256
	s_nop 0
	s_add_u32 m0, s100, 12544
	s_nop 0
	global_load_lds_dwordx4 v[88:89], off offset:256
	v_addc_co_u32_e32 v97, vcc, 0, v135, vcc
	v_add_co_u32_e32 v104, vcc, 0x1980000, v134
	s_nop 1
	v_addc_co_u32_e32 v105, vcc, 0, v135, vcc
	v_add_co_u32_e32 v112, vcc, 0x19c0000, v134
	s_add_u32 m0, s100, 16640
	s_nop 0
	global_load_lds_dwordx4 v[96:97], off offset:256
	s_nop 0
	s_add_u32 m0, s100, 20736
	s_nop 0
	global_load_lds_dwordx4 v[104:105], off offset:256
	v_addc_co_u32_e32 v113, vcc, 0, v135, vcc
	v_add_co_u32_e32 v120, vcc, 0x1a00000, v134
	s_nop 1
	v_addc_co_u32_e32 v121, vcc, 0, v135, vcc
	s_add_u32 m0, s100, 24832
	s_nop 0
	global_load_lds_dwordx4 v[112:113], off offset:256
	s_nop 0
	s_add_u32 m0, s100, 28928
	s_nop 0
	global_load_lds_dwordx4 v[120:121], off offset:256
	s_branch .LBB0_1222
